# phase C sel/window: hand-scheduled chunk body for the fixed-reference case, QK(h+2)/PV(h-1) MFMAs interleaved with head h exp/cvt/sum
# speedup vs baseline: 1.0143x; 1.0143x over previous
; #define MFMA16(a, b, c) __builtin_amdgcn_mfma_f32_16x16x32_bf16((a), (b), (c), 0, 0, 0)
; template <int MODE>
; DI void nsa_chunk(const KVFrag& f, int kb, int t, bool selbit, const bf16x8 (&qf)[4][2], f32x4 (&O)[4][4], float (&m)[4], float (&l)[4], int quad, bool online) {
;     ...
;   bool val[8];
; #pragma unroll
;   for (int idx = 0; idx < 8; ++idx) {
;     const int key = kb + 8 * quad + idx;
;     val[idx] = MODE == 0 ? (selbit && key <= t) : (key <= t && key > t - 512);
;   }
; #pragma unroll
;   for (int hh = 0; hh < 4; ++hh) {
;     f32x4 s[2];
; #pragma unroll
;     for (int a = 0; a < 2; ++a) { s[a] = MFMA16(f.k[a][0], qf[hh][0], ((f32x4){0.f, 0.f, 0.f, 0.f})); s[a] = MFMA16(f.k[a][1], qf[hh][1], s[a]); }
;     float mn = m[hh];
;     if (online) {
;       float cm = -1e30f;
; #pragma unroll
;       for (int idx = 0; idx < 8; ++idx) if (val[idx]) cm = fmaxf(cm, s[idx >> 2][idx & 3] * SC);
;       cm = fmaxf(cm, __shfl_xor(cm, 16)); cm = fmaxf(cm, __shfl_xor(cm, 32));
;       mn = fmaxf(mn, cm);
;       const float alpha = __builtin_amdgcn_exp2f(m[hh] - mn);
;       m[hh] = mn; l[hh] *= alpha;
; #pragma unroll
;       for (int dt = 0; dt < 4; ++dt) O[hh][dt] = O[hh][dt] * alpha;
;     }
; template <int MODE>
; DI void nsa_branch(const bf16_t* __restrict__ Kb, const bf16_t* __restrict__ Vtb, unsigned char* lds, int nb, int t, int cur, unsigned selmask, unsigned umall,
;                    const bf16x8 (&qf)[4][2], f32x4 (&O)[4][4], float (&m)[4], float (&l)[4], bool online) {
;     ...
;   for (int n = 0; n < N; n += 2) {
;     const int j = blist[n >> 1];
;     const bool won = MODE == 0 ? ((umall >> j) & 1u) != 0 : (j >= cur - 8 && j <= cur);
;     const bool bit = (selmask >> j) & 1u;
;     ra = *(const u32x4*)(gsrc + (long)kbof(min(n + 2, N - 2)) * gmul);
;     if (won) { KVFrag f; nsa_ldsfrag(f, slot0, qi, quad); nsa_chunk<MODE>(f, j * 64, t, bit, qf, O, m, l, quad, online); }
.LBB0_727:
	s_sub_u32 s58, s56, 0x14c20
	s_lshr_b32 s58, s58, 2
	v_readlane_b32 s0, v216, s58
	s_nop 1
	v_mov_b32_e32 v181, s0
	s_lshl_b32 s10, 1, s0
	s_and_b32 s11, s10, s42
	s_cmp_lg_u32 s11, 0
	s_cselect_b64 s[0:1], -1, 0
	s_add_i32 s57, s54, -1
	s_min_i32 s12, s57, s43
	s_lshr_b32 s12, s12, 1
	v_readlane_b32 s58, v216, s12
	v_and_b32_e32 v116, s10, v171
	v_cmp_ne_u32_e64 s[12:13], 0, v116
	v_cndmask_b32_e64 v116, 0, 1, s[8:9]
	s_lshl_b32 s58, s58, 6
	s_ashr_i32 s59, s58, 31
	s_lshl_b64 s[58:59], s[58:59], 7
	s_cmp_eq_u32 s11, 0
	v_lshl_add_u64 v[112:113], v[168:169], 0, s[58:59]
	global_load_dwordx4 v[112:115], v[112:113], off
	v_cmp_ne_u32_e64 s[10:11], 1, v116
	s_cbranch_scc1 .LBB0_737
	v_lshl_or_b32 v182, v181, 6, v173
	v_cmp_le_i32_e32 vcc, v182, v160
	s_and_b64 s[16:17], s[12:13], vcc
	v_cmp_lt_i32_e32 vcc, v182, v160
	v_or_b32_e32 v148, 2, v182
	s_and_b64 s[18:19], s[12:13], vcc
	v_cmp_le_i32_e32 vcc, v148, v160
	v_or_b32_e32 v148, 3, v182
	s_and_b64 s[44:45], s[12:13], vcc
	v_cmp_le_i32_e32 vcc, v148, v160
	v_or_b32_e32 v148, 4, v182
	ds_read_b128 v[136:139], v176
	ds_read_b128 v[140:143], v176 offset:64
	ds_read_b128 v[144:147], v176 offset:576
	ds_read_b128 v[132:135], v176 offset:640
	ds_read_b128 v[128:131], v177
	ds_read_b128 v[124:127], v177 offset:1280
	ds_read_b128 v[120:123], v177 offset:2560
	ds_read_b128 v[116:119], v177 offset:3840
	s_and_b64 s[46:47], s[12:13], vcc
	v_cmp_le_i32_e32 vcc, v148, v160
	v_or_b32_e32 v152, 5, v182
	s_and_b64 s[14:15], s[12:13], vcc
	v_cmp_le_i32_e32 vcc, v152, v160
	v_or_b32_e32 v183, 6, v182
	s_and_b64 s[48:49], s[12:13], vcc
	v_cmp_le_i32_e32 vcc, v183, v160
	v_or_b32_e32 v182, 7, v182
	s_and_b64 s[50:51], s[12:13], vcc
	v_cmp_le_i32_e32 vcc, v182, v160
	s_and_b64 s[52:53], s[12:13], vcc
	s_and_b64 vcc, exec, s[10:11]
	v_mov_b32_e32 v226, 0xff800000
	v_cndmask_b32_e64 v218, v226, 0, s[16:17]
	v_cndmask_b32_e64 v219, v226, 0, s[18:19]
	v_cndmask_b32_e64 v220, v226, 0, s[44:45]
	v_cndmask_b32_e64 v221, v226, 0, s[46:47]
	v_cndmask_b32_e64 v222, v226, 0, s[14:15]
	v_cndmask_b32_e64 v223, v226, 0, s[48:49]
	v_cndmask_b32_e64 v224, v226, 0, s[50:51]
	v_cndmask_b32_e64 v225, v226, 0, s[52:53]
	s_nop 1
	s_cbranch_vccnz .Lmy_fast_s1
	s_waitcnt lgkmcnt(7)
	v_mfma_f32_16x16x32_bf16 v[148:151], v[136:139], v[8:11], v[218:221]
	s_waitcnt lgkmcnt(6)
	v_mfma_f32_16x16x32_bf16 v[152:155], v[140:143], v[12:15], v[148:151]
	s_waitcnt lgkmcnt(5)
	v_mfma_f32_16x16x32_bf16 v[148:151], v[144:147], v[8:11], v[222:225]
	s_waitcnt lgkmcnt(4)
	v_mfma_f32_16x16x32_bf16 v[148:151], v[132:135], v[12:15], v[148:151]
	s_nop 7
	s_cbranch_vccnz .LBB0_730
	v_mul_f32_e32 v182, 0x3e38aa3b, v152
	v_max_f32_e32 v182, 0xf149f2ca, v182
	v_cndmask_b32_e64 v182, v232, v182, s[16:17]
	v_mul_f32_e32 v183, 0x3e38aa3b, v153
	v_max_f32_e32 v183, v182, v183
	v_cndmask_b32_e64 v182, v182, v183, s[18:19]
	v_mul_f32_e32 v183, 0x3e38aa3b, v154
	v_max_f32_e32 v183, v182, v183
	v_cndmask_b32_e64 v182, v182, v183, s[44:45]
	v_mul_f32_e32 v183, 0x3e38aa3b, v155
	v_max_f32_e32 v183, v182, v183
	v_cndmask_b32_e64 v182, v182, v183, s[46:47]
	v_mul_f32_e32 v183, 0x3e38aa3b, v148
	v_max_f32_e32 v183, v182, v183
	v_cndmask_b32_e64 v182, v182, v183, s[14:15]
	v_mul_f32_e32 v183, 0x3e38aa3b, v149
	v_max_f32_e32 v184, v182, v182
	v_max_f32_e32 v183, v184, v183
	v_cndmask_b32_e64 v182, v182, v183, s[48:49]
	v_mul_f32_e32 v183, 0x3e38aa3b, v150
	v_max_f32_e32 v184, v182, v182
	v_max_f32_e32 v183, v184, v183
	v_cndmask_b32_e64 v182, v182, v183, s[50:51]
	v_mul_f32_e32 v183, 0x3e38aa3b, v151
	v_max_f32_e32 v184, v182, v182
	v_max_f32_e32 v183, v184, v183
	v_cndmask_b32_e64 v182, v182, v183, s[52:53]
	ds_bpermute_b32 v183, v175, v182
	v_max_f32_e32 v182, v182, v182
	s_waitcnt lgkmcnt(0)
	v_max_f32_e32 v183, v183, v183
	v_max_f32_e32 v182, v182, v183
	ds_bpermute_b32 v183, v159, v182
	s_waitcnt lgkmcnt(0)
	v_max3_f32 v183, v3, v182, v183
	v_sub_f32_e32 v3, v3, v183
	v_exp_f32_e32 v182, v3
	v_mov_b32_e32 v3, v183
	v_mul_f32_e32 v167, v167, v182
	v_pk_mul_f32 v[106:107], v[106:107], v[182:183] op_sel_hi:[1,0]
	v_pk_mul_f32 v[104:105], v[104:105], v[182:183] op_sel_hi:[1,0]
	v_pk_mul_f32 v[102:103], v[102:103], v[182:183] op_sel_hi:[1,0]
	v_pk_mul_f32 v[100:101], v[100:101], v[182:183] op_sel_hi:[1,0]
	v_pk_mul_f32 v[98:99], v[98:99], v[182:183] op_sel_hi:[1,0]
	v_pk_mul_f32 v[96:97], v[96:97], v[182:183] op_sel_hi:[1,0]
	v_pk_mul_f32 v[94:95], v[94:95], v[182:183] op_sel_hi:[1,0]
	v_pk_mul_f32 v[92:93], v[92:93], v[182:183] op_sel_hi:[1,0]

; #define MFMA16(a, b, c) __builtin_amdgcn_mfma_f32_16x16x32_bf16((a), (b), (c), 0, 0, 0)
; template <int MODE>
; DI void nsa_chunk(const KVFrag& f, int kb, int t, bool selbit, const bf16x8 (&qf)[4][2], f32x4 (&O)[4][4], float (&m)[4], float (&l)[4], int quad, bool online) {
;     ...
;   bool val[8];
; #pragma unroll
;   for (int idx = 0; idx < 8; ++idx) {
;     const int key = kb + 8 * quad + idx;
;     val[idx] = MODE == 0 ? (selbit && key <= t) : (key <= t && key > t - 512);
;   }
; #pragma unroll
;   for (int hh = 0; hh < 4; ++hh) {
;     f32x4 s[2];
; #pragma unroll
;     for (int a = 0; a < 2; ++a) { s[a] = MFMA16(f.k[a][0], qf[hh][0], ((f32x4){0.f, 0.f, 0.f, 0.f})); s[a] = MFMA16(f.k[a][1], qf[hh][1], s[a]); }
;     float mn = m[hh];
;     if (online) {
;       float cm = -1e30f;
; #pragma unroll
;       for (int idx = 0; idx < 8; ++idx) if (val[idx]) cm = fmaxf(cm, s[idx >> 2][idx & 3] * SC);
;       cm = fmaxf(cm, __shfl_xor(cm, 16)); cm = fmaxf(cm, __shfl_xor(cm, 32));
;       mn = fmaxf(mn, cm);
;       const float alpha = __builtin_amdgcn_exp2f(m[hh] - mn);
;       m[hh] = mn; l[hh] *= alpha;
; #pragma unroll
;       for (int dt = 0; dt < 4; ++dt) O[hh][dt] = O[hh][dt] * alpha;
;     }
; template <int MODE>
; DI void nsa_branch(const bf16_t* __restrict__ Kb, const bf16_t* __restrict__ Vtb, unsigned char* lds, int nb, int t, int cur, unsigned selmask, unsigned umall,
;                    const bf16x8 (&qf)[4][2], f32x4 (&O)[4][4], float (&m)[4], float (&l)[4], bool online) {
;     ...
;     *(u32x4*)(slot1 + ldst) = rb;
;     __syncthreads();
;     rb = *(const u32x4*)(gsrc + (long)kbof(min(n + 3, N - 1)) * gmul);
;     if (won) { KVFrag f; nsa_ldsfrag(f, slot1, qi, quad); nsa_chunk<MODE>(f, j * 64 + 32, t, bit, qf, O, m, l, quad, online); }
.LBB0_737:
	s_min_i32 s14, s54, s55
	s_lshr_b32 s14, s14, 1
	v_add_u32_e32 v116, 0x12600, v161
	s_waitcnt vmcnt(1)
	ds_write_b128 v116, v[108:111]
	s_waitcnt lgkmcnt(0)
	s_barrier
	v_readlane_b32 s14, v216, s14
	s_andn2_b64 vcc, exec, s[0:1]
	s_lshl_b32 s14, s14, 6
	s_or_b32 s14, s14, 32
	s_ashr_i32 s15, s14, 31
	s_lshl_b64 s[14:15], s[14:15], 7
	v_lshl_add_u64 v[108:109], v[168:169], 0, s[14:15]
	global_load_dwordx4 v[108:111], v[108:109], off
	s_cbranch_vccnz .LBB0_726
	v_lshl_or_b32 v181, v181, 6, v174
	v_cmp_le_i32_e32 vcc, v181, v160
	s_and_b64 s[16:17], s[12:13], vcc
	v_cmp_lt_i32_e32 vcc, v181, v160
	v_or_b32_e32 v148, 2, v181
	s_and_b64 s[18:19], s[12:13], vcc
	v_cmp_le_i32_e32 vcc, v148, v160
	v_or_b32_e32 v148, 3, v181
	s_and_b64 s[44:45], s[12:13], vcc
	v_cmp_le_i32_e32 vcc, v148, v160
	v_or_b32_e32 v148, 4, v181
	ds_read_b128 v[136:139], v178
	ds_read_b128 v[140:143], v178 offset:64
	ds_read_b128 v[144:147], v178 offset:576
	ds_read_b128 v[132:135], v178 offset:640
	ds_read_b128 v[128:131], v179
	ds_read_b128 v[124:127], v179 offset:1280
	ds_read_b128 v[120:123], v179 offset:2560
	ds_read_b128 v[116:119], v179 offset:3840
	s_and_b64 s[46:47], s[12:13], vcc
	v_cmp_le_i32_e32 vcc, v148, v160
	v_or_b32_e32 v152, 5, v181
	s_and_b64 s[14:15], s[12:13], vcc
	v_cmp_le_i32_e32 vcc, v152, v160
	v_or_b32_e32 v182, 6, v181
	s_and_b64 s[48:49], s[12:13], vcc
	v_cmp_le_i32_e32 vcc, v182, v160
	v_or_b32_e32 v181, 7, v181
	s_and_b64 s[50:51], s[12:13], vcc
	v_cmp_le_i32_e32 vcc, v181, v160
	s_and_b64 s[12:13], s[12:13], vcc
	s_and_b64 vcc, exec, s[10:11]
	v_mov_b32_e32 v226, 0xff800000
	v_cndmask_b32_e64 v218, v226, 0, s[16:17]
	v_cndmask_b32_e64 v219, v226, 0, s[18:19]
	v_cndmask_b32_e64 v220, v226, 0, s[44:45]
	v_cndmask_b32_e64 v221, v226, 0, s[46:47]
	v_cndmask_b32_e64 v222, v226, 0, s[14:15]
	v_cndmask_b32_e64 v223, v226, 0, s[48:49]
	v_cndmask_b32_e64 v224, v226, 0, s[50:51]
	v_cndmask_b32_e64 v225, v226, 0, s[12:13]
	s_nop 1
	s_cbranch_vccnz .Lmy_fast_s2
	s_waitcnt lgkmcnt(7)
	v_mfma_f32_16x16x32_bf16 v[148:151], v[136:139], v[8:11], v[218:221]
	s_waitcnt lgkmcnt(6)
	v_mfma_f32_16x16x32_bf16 v[152:155], v[140:143], v[12:15], v[148:151]
	s_waitcnt lgkmcnt(5)
	v_mfma_f32_16x16x32_bf16 v[148:151], v[144:147], v[8:11], v[222:225]
	s_waitcnt lgkmcnt(4)
	v_mfma_f32_16x16x32_bf16 v[148:151], v[132:135], v[12:15], v[148:151]
	s_nop 7
	s_cbranch_vccnz .LBB0_740
	v_mul_f32_e32 v181, 0x3e38aa3b, v152
	v_max_f32_e32 v181, 0xf149f2ca, v181
	v_cndmask_b32_e64 v181, v232, v181, s[16:17]
	v_mul_f32_e32 v182, 0x3e38aa3b, v153
	v_max_f32_e32 v182, v181, v182
	v_cndmask_b32_e64 v181, v181, v182, s[18:19]
	v_mul_f32_e32 v182, 0x3e38aa3b, v154
	v_max_f32_e32 v182, v181, v182
	v_cndmask_b32_e64 v181, v181, v182, s[44:45]
	v_mul_f32_e32 v182, 0x3e38aa3b, v155
	v_max_f32_e32 v182, v181, v182
	v_cndmask_b32_e64 v181, v181, v182, s[46:47]
	v_mul_f32_e32 v182, 0x3e38aa3b, v148
	v_max_f32_e32 v182, v181, v182
	v_cndmask_b32_e64 v181, v181, v182, s[14:15]
	v_mul_f32_e32 v182, 0x3e38aa3b, v149
	v_max_f32_e32 v183, v181, v181
	v_max_f32_e32 v182, v183, v182
	v_cndmask_b32_e64 v181, v181, v182, s[48:49]
	v_mul_f32_e32 v182, 0x3e38aa3b, v150
	v_max_f32_e32 v183, v181, v181
	v_max_f32_e32 v182, v183, v182
	v_cndmask_b32_e64 v181, v181, v182, s[50:51]
	v_mul_f32_e32 v182, 0x3e38aa3b, v151
	v_max_f32_e32 v183, v181, v181
	v_max_f32_e32 v182, v183, v182
	v_cndmask_b32_e64 v181, v181, v182, s[12:13]
	ds_bpermute_b32 v182, v175, v181
	v_max_f32_e32 v181, v181, v181
	s_waitcnt lgkmcnt(0)
	v_max_f32_e32 v182, v182, v182
	v_max_f32_e32 v181, v181, v182
	ds_bpermute_b32 v182, v159, v181
	s_waitcnt lgkmcnt(0)
	v_max3_f32 v181, v3, v181, v182
	v_sub_f32_e32 v3, v3, v181
	v_exp_f32_e32 v182, v3
	v_mov_b32_e32 v3, v181
	v_mul_f32_e32 v167, v167, v182
	v_pk_mul_f32 v[106:107], v[106:107], v[182:183] op_sel_hi:[1,0]
	v_pk_mul_f32 v[104:105], v[104:105], v[182:183] op_sel_hi:[1,0]
	v_pk_mul_f32 v[102:103], v[102:103], v[182:183] op_sel_hi:[1,0]
	v_pk_mul_f32 v[100:101], v[100:101], v[182:183] op_sel_hi:[1,0]
	v_pk_mul_f32 v[98:99], v[98:99], v[182:183] op_sel_hi:[1,0]
	v_pk_mul_f32 v[96:97], v[96:97], v[182:183] op_sel_hi:[1,0]
	v_pk_mul_f32 v[94:95], v[94:95], v[182:183] op_sel_hi:[1,0]
	v_pk_mul_f32 v[92:93], v[92:93], v[182:183] op_sel_hi:[1,0]

; #define MFMA16(a, b, c) __builtin_amdgcn_mfma_f32_16x16x32_bf16((a), (b), (c), 0, 0, 0)
; DI unsigned pk2(float lo, float hi) { f32x2 v = {lo, hi}; bf16x2_t b = __builtin_convertvector(v, bf16x2_t); return __builtin_bit_cast(unsigned, b); }
; template <int MODE>
; DI void nsa_chunk(const KVFrag& f, int kb, int t, bool selbit, const bf16x8 (&qf)[4][2], f32x4 (&O)[4][4], float (&m)[4], float (&l)[4], int quad, bool online) {
;     ...
;   for (int hh = 0; hh < 4; ++hh) {
;     f32x4 s[2];
; #pragma unroll
;     for (int a = 0; a < 2; ++a) { s[a] = MFMA16(f.k[a][0], qf[hh][0], ((f32x4){0.f, 0.f, 0.f, 0.f})); s[a] = MFMA16(f.k[a][1], qf[hh][1], s[a]); }
;     float mn = m[hh];
;     if (online) {
;       float cm = -1e30f;
; #pragma unroll
;       for (int idx = 0; idx < 8; ++idx) if (val[idx]) cm = fmaxf(cm, s[idx >> 2][idx & 3] * SC);
;       cm = fmaxf(cm, __shfl_xor(cm, 16)); cm = fmaxf(cm, __shfl_xor(cm, 32));
;       mn = fmaxf(mn, cm);
;       const float alpha = __builtin_amdgcn_exp2f(m[hh] - mn);
;       m[hh] = mn; l[hh] *= alpha;
; #pragma unroll
;       for (int dt = 0; dt < 4; ++dt) O[hh][dt] = O[hh][dt] * alpha;
;     }
;     float pv[8]; float ps = 0.f;
; #pragma unroll
;     for (int idx = 0; idx < 8; ++idx) { pv[idx] = val[idx] ? __builtin_amdgcn_exp2f(fmaf(s[idx >> 2][idx & 3], SC, -mn)) : 0.f; ps += pv[idx]; }
;     l[hh] += ps;
;     const bf16x8 pf = mk8((u32x4){pk2(pv[0], pv[1]), pk2(pv[2], pv[3]), pk2(pv[4], pv[5]), pk2(pv[6], pv[7])});
; #pragma unroll
;     for (int dt = 0; dt < 4; ++dt) O[hh][dt] = MFMA16(f.v[dt], pf, O[hh][dt]);
;   }
.Lmy_fast_s1:
	s_waitcnt lgkmcnt(4)
	v_mfma_f32_16x16x32_bf16 v[182:185], v[136:139], v[8:11], v[218:221]
	v_mfma_f32_16x16x32_bf16 v[182:185], v[140:143], v[12:15], v[182:185]
	v_mfma_f32_16x16x32_bf16 v[186:189], v[144:147], v[8:11], v[222:225]
	v_mfma_f32_16x16x32_bf16 v[186:189], v[132:135], v[12:15], v[186:189]
	v_mfma_f32_16x16x32_bf16 v[190:193], v[136:139], v[16:19], v[218:221]
	v_mfma_f32_16x16x32_bf16 v[190:193], v[140:143], v[20:23], v[190:193]
	v_mfma_f32_16x16x32_bf16 v[194:197], v[144:147], v[16:19], v[222:225]
	v_mfma_f32_16x16x32_bf16 v[194:197], v[132:135], v[20:23], v[194:197]
	s_waitcnt lgkmcnt(0)
	s_nop 2
	v_pk_fma_f32 v[240:241], v[182:183], s[34:35], v[2:3] op_sel:[0,0,1] op_sel_hi:[1,0,1] neg_lo:[0,0,1] neg_hi:[0,0,1]
	v_pk_fma_f32 v[242:243], v[184:185], s[34:35], v[2:3] op_sel:[0,0,1] op_sel_hi:[1,0,1] neg_lo:[0,0,1] neg_hi:[0,0,1]
	v_pk_fma_f32 v[244:245], v[186:187], s[34:35], v[2:3] op_sel:[0,0,1] op_sel_hi:[1,0,1] neg_lo:[0,0,1] neg_hi:[0,0,1]
	v_pk_fma_f32 v[246:247], v[188:189], s[34:35], v[2:3] op_sel:[0,0,1] op_sel_hi:[1,0,1] neg_lo:[0,0,1] neg_hi:[0,0,1]
	v_exp_f32_e32 v240, v240
	v_exp_f32_e32 v241, v241
	v_mfma_f32_16x16x32_bf16 v[182:185], v[136:139], v[24:27], v[218:221]
	v_exp_f32_e32 v242, v242
	v_exp_f32_e32 v243, v243
	v_mfma_f32_16x16x32_bf16 v[182:185], v[140:143], v[28:31], v[182:185]
	v_exp_f32_e32 v244, v244
	v_exp_f32_e32 v245, v245
	v_mfma_f32_16x16x32_bf16 v[186:189], v[144:147], v[24:27], v[222:225]
	v_exp_f32_e32 v246, v246
	v_exp_f32_e32 v247, v247
	v_mfma_f32_16x16x32_bf16 v[186:189], v[132:135], v[28:31], v[186:189]
	v_cvt_pk_bf16_f32 v248, v240, v241
	v_cvt_pk_bf16_f32 v249, v242, v243
	v_cvt_pk_bf16_f32 v250, v244, v245
	v_cvt_pk_bf16_f32 v251, v246, v247
	v_add_f32_e32 v205, 0, v240
	v_add_f32_e32 v205, v241, v205
	v_add_f32_e32 v205, v242, v205
	v_add_f32_e32 v205, v243, v205
	v_add_f32_e32 v205, v244, v205
	v_add_f32_e32 v205, v245, v205
	v_add_f32_e32 v205, v246, v205
	v_add_f32_e32 v205, v247, v205
	v_add_f32_e32 v167, v167, v205
	v_pk_fma_f32 v[240:241], v[190:191], s[34:35], v[2:3] op_sel_hi:[1,0,0] neg_lo:[0,0,1] neg_hi:[0,0,1]
	v_pk_fma_f32 v[242:243], v[192:193], s[34:35], v[2:3] op_sel_hi:[1,0,0] neg_lo:[0,0,1] neg_hi:[0,0,1]
	v_pk_fma_f32 v[244:245], v[194:195], s[34:35], v[2:3] op_sel_hi:[1,0,0] neg_lo:[0,0,1] neg_hi:[0,0,1]
	v_pk_fma_f32 v[246:247], v[196:197], s[34:35], v[2:3] op_sel_hi:[1,0,0] neg_lo:[0,0,1] neg_hi:[0,0,1]
	v_exp_f32_e32 v240, v240
	v_exp_f32_e32 v241, v241
	v_mfma_f32_16x16x32_bf16 v[190:193], v[136:139], v[32:35], v[218:221]
	v_exp_f32_e32 v242, v242
	v_exp_f32_e32 v243, v243
	v_mfma_f32_16x16x32_bf16 v[190:193], v[140:143], v[36:39], v[190:193]
	v_exp_f32_e32 v244, v244
	v_exp_f32_e32 v245, v245
	v_mfma_f32_16x16x32_bf16 v[194:197], v[144:147], v[32:35], v[222:225]
	v_exp_f32_e32 v246, v246
	v_exp_f32_e32 v247, v247
	v_mfma_f32_16x16x32_bf16 v[194:197], v[132:135], v[36:39], v[194:197]
	v_cvt_pk_bf16_f32 v198, v240, v241
	v_cvt_pk_bf16_f32 v199, v242, v243
	v_mfma_f32_16x16x32_bf16 v[104:107], v[128:131], v[248:251], v[104:107]
	v_cvt_pk_bf16_f32 v200, v244, v245
	v_cvt_pk_bf16_f32 v201, v246, v247
	v_mfma_f32_16x16x32_bf16 v[100:103], v[124:127], v[248:251], v[100:103]
	v_add_f32_e32 v205, 0, v240
	v_add_f32_e32 v205, v241, v205
	v_mfma_f32_16x16x32_bf16 v[96:99], v[120:123], v[248:251], v[96:99]
	v_add_f32_e32 v205, v242, v205
	v_add_f32_e32 v205, v243, v205
	v_mfma_f32_16x16x32_bf16 v[92:95], v[116:119], v[248:251], v[92:95]
	v_add_f32_e32 v205, v244, v205
	v_add_f32_e32 v205, v245, v205
	v_add_f32_e32 v205, v246, v205
	v_add_f32_e32 v205, v247, v205
	v_add_f32_e32 v166, v166, v205
	v_pk_fma_f32 v[240:241], v[182:183], s[34:35], v[0:1] op_sel_hi:[1,0,0] neg_lo:[0,0,1] neg_hi:[0,0,1]
	v_pk_fma_f32 v[242:243], v[184:185], s[34:35], v[0:1] op_sel_hi:[1,0,0] neg_lo:[0,0,1] neg_hi:[0,0,1]
	v_pk_fma_f32 v[244:245], v[186:187], s[34:35], v[0:1] op_sel_hi:[1,0,0] neg_lo:[0,0,1] neg_hi:[0,0,1]
	v_pk_fma_f32 v[246:247], v[188:189], s[34:35], v[0:1] op_sel_hi:[1,0,0] neg_lo:[0,0,1] neg_hi:[0,0,1]
	v_exp_f32_e32 v240, v240
	v_exp_f32_e32 v241, v241
	v_mfma_f32_16x16x32_bf16 v[88:91], v[128:131], v[198:201], v[88:91]
	v_exp_f32_e32 v242, v242
	v_exp_f32_e32 v243, v243
	v_mfma_f32_16x16x32_bf16 v[84:87], v[124:127], v[198:201], v[84:87]
	v_exp_f32_e32 v244, v244
	v_exp_f32_e32 v245, v245
	v_mfma_f32_16x16x32_bf16 v[80:83], v[120:123], v[198:201], v[80:83]
	v_exp_f32_e32 v246, v246
	v_exp_f32_e32 v247, v247
	v_mfma_f32_16x16x32_bf16 v[76:79], v[116:119], v[198:201], v[76:79]
	v_cvt_pk_bf16_f32 v248, v240, v241
	v_cvt_pk_bf16_f32 v249, v242, v243
	v_cvt_pk_bf16_f32 v250, v244, v245
	v_cvt_pk_bf16_f32 v251, v246, v247
	v_add_f32_e32 v205, 0, v240
	v_add_f32_e32 v205, v241, v205
	v_add_f32_e32 v205, v242, v205
	v_add_f32_e32 v205, v243, v205
	v_add_f32_e32 v205, v244, v205
	v_add_f32_e32 v205, v245, v205
	v_add_f32_e32 v205, v246, v205
	v_add_f32_e32 v205, v247, v205
	v_add_f32_e32 v165, v165, v205
	v_pk_fma_f32 v[240:241], v[190:191], s[34:35], v[180:181] op_sel_hi:[1,0,0] neg_lo:[0,0,1] neg_hi:[0,0,1]
	v_pk_fma_f32 v[242:243], v[192:193], s[34:35], v[180:181] op_sel_hi:[1,0,0] neg_lo:[0,0,1] neg_hi:[0,0,1]
	v_pk_fma_f32 v[244:245], v[194:195], s[34:35], v[180:181] op_sel_hi:[1,0,0] neg_lo:[0,0,1] neg_hi:[0,0,1]
	v_pk_fma_f32 v[246:247], v[196:197], s[34:35], v[180:181] op_sel_hi:[1,0,0] neg_lo:[0,0,1] neg_hi:[0,0,1]
	v_exp_f32_e32 v240, v240
	v_exp_f32_e32 v241, v241
	v_mfma_f32_16x16x32_bf16 v[72:75], v[128:131], v[248:251], v[72:75]
	v_exp_f32_e32 v242, v242
	v_exp_f32_e32 v243, v243
	v_mfma_f32_16x16x32_bf16 v[68:71], v[124:127], v[248:251], v[68:71]
	v_exp_f32_e32 v244, v244
	v_exp_f32_e32 v245, v245
	v_mfma_f32_16x16x32_bf16 v[64:67], v[120:123], v[248:251], v[64:67]
	v_exp_f32_e32 v246, v246
	v_exp_f32_e32 v247, v247
	v_mfma_f32_16x16x32_bf16 v[60:63], v[116:119], v[248:251], v[60:63]
	v_cvt_pk_bf16_f32 v198, v240, v241
	v_cvt_pk_bf16_f32 v199, v242, v243
	v_cvt_pk_bf16_f32 v200, v244, v245
	v_cvt_pk_bf16_f32 v201, v246, v247
	v_add_f32_e32 v205, 0, v240
	v_add_f32_e32 v205, v241, v205
	v_add_f32_e32 v205, v242, v205
	v_add_f32_e32 v205, v243, v205
	v_add_f32_e32 v205, v244, v205
	v_add_f32_e32 v205, v245, v205
	v_add_f32_e32 v205, v246, v205
	v_add_f32_e32 v205, v247, v205
	v_add_f32_e32 v164, v164, v205
	s_nop 0
	v_mfma_f32_16x16x32_bf16 v[56:59], v[128:131], v[198:201], v[56:59]
	v_mfma_f32_16x16x32_bf16 v[52:55], v[124:127], v[198:201], v[52:55]
	v_mfma_f32_16x16x32_bf16 v[48:51], v[120:123], v[198:201], v[48:51]
	v_mfma_f32_16x16x32_bf16 v[44:47], v[116:119], v[198:201], v[44:47]
	s_branch .LBB0_737

; #define MFMA16(a, b, c) __builtin_amdgcn_mfma_f32_16x16x32_bf16((a), (b), (c), 0, 0, 0)
; template <int MODE>
; DI void nsa_chunk(const KVFrag& f, int kb, int t, bool selbit, const bf16x8 (&qf)[4][2], f32x4 (&O)[4][4], float (&m)[4], float (&l)[4], int quad, bool online) {
;     ...
;   bool val[8];
; #pragma unroll
;   for (int idx = 0; idx < 8; ++idx) {
;     const int key = kb + 8 * quad + idx;
;     val[idx] = MODE == 0 ? (selbit && key <= t) : (key <= t && key > t - 512);
;   }
; #pragma unroll
;   for (int hh = 0; hh < 4; ++hh) {
;     f32x4 s[2];
; #pragma unroll
;     for (int a = 0; a < 2; ++a) { s[a] = MFMA16(f.k[a][0], qf[hh][0], ((f32x4){0.f, 0.f, 0.f, 0.f})); s[a] = MFMA16(f.k[a][1], qf[hh][1], s[a]); }
;     float mn = m[hh];
;     if (online) {
;       float cm = -1e30f;
; #pragma unroll
;       for (int idx = 0; idx < 8; ++idx) if (val[idx]) cm = fmaxf(cm, s[idx >> 2][idx & 3] * SC);
;       cm = fmaxf(cm, __shfl_xor(cm, 16)); cm = fmaxf(cm, __shfl_xor(cm, 32));
;       mn = fmaxf(mn, cm);
;       const float alpha = __builtin_amdgcn_exp2f(m[hh] - mn);
;       m[hh] = mn; l[hh] *= alpha;
; #pragma unroll
;       for (int dt = 0; dt < 4; ++dt) O[hh][dt] = O[hh][dt] * alpha;
;     }
; template <int MODE>
; DI void nsa_branch(const bf16_t* __restrict__ Kb, const bf16_t* __restrict__ Vtb, unsigned char* lds, int nb, int t, int cur, unsigned selmask, unsigned umall,
;                    const bf16x8 (&qf)[4][2], f32x4 (&O)[4][4], float (&m)[4], float (&l)[4], bool online) {
;     ...
;   for (int n = 0; n < N; n += 2) {
;     const int j = blist[n >> 1];
;     const bool won = MODE == 0 ? ((umall >> j) & 1u) != 0 : (j >= cur - 8 && j <= cur);
;     const bool bit = (selmask >> j) & 1u;
;     ra = *(const u32x4*)(gsrc + (long)kbof(min(n + 2, N - 2)) * gmul);
;     if (won) { KVFrag f; nsa_ldsfrag(f, slot0, qi, quad); nsa_chunk<MODE>(f, j * 64, t, bit, qf, O, m, l, quad, online); }
.LBB0_757:
	v_mov_b32_e32 v108, s30
	s_add_i32 s36, s28, -1
	ds_read_b32 v180, v108
	v_min_i32_e32 v108, s36, v168
	v_lshl_add_u32 v108, v108, 1, 32
	v_add_u32_e32 v108, 0x14c00, v108
	ds_read_b32 v108, v108
	s_waitcnt lgkmcnt(1)
	v_cmp_ge_i32_e32 vcc, v180, v156
	v_cmp_le_i32_e64 s[0:1], v180, v170
	v_cndmask_b32_e64 v112, 0, 1, s[44:45]
	s_and_b64 s[54:55], vcc, s[0:1]
	s_waitcnt lgkmcnt(0)
	v_lshlrev_b32_e32 v108, 6, v108
	v_ashrrev_i32_e32 v109, 31, v108
	v_lshlrev_b64 v[108:109], 7, v[108:109]
	v_lshl_add_u64 v[108:109], v[164:165], 0, v[108:109]
	global_load_dwordx4 v[108:111], v[108:109], off
	v_cmp_ne_u32_e64 s[8:9], 1, v112
	s_and_saveexec_b64 s[56:57], s[54:55]
	s_cbranch_execz .LBB0_767
	v_lshl_or_b32 v181, v180, 6, v169
	v_cmp_le_i32_e32 vcc, v181, v160
	v_cmp_gt_i32_e64 s[0:1], v181, v171
	s_and_b64 s[10:11], vcc, s[0:1]
	v_cmp_lt_i32_e32 vcc, v181, v160
	v_cmp_ge_i32_e64 s[0:1], v181, v171
	v_or_b32_e32 v144, 2, v181
	s_and_b64 s[14:15], vcc, s[0:1]
	v_cmp_le_i32_e32 vcc, v144, v160
	v_cmp_gt_i32_e64 s[0:1], v144, v171
	v_or_b32_e32 v144, 3, v181
	s_and_b64 s[18:19], vcc, s[0:1]
	v_cmp_le_i32_e32 vcc, v144, v160
	v_cmp_gt_i32_e64 s[0:1], v144, v171
	v_or_b32_e32 v144, 4, v181
	s_and_b64 s[46:47], vcc, s[0:1]
	v_cmp_le_i32_e32 vcc, v144, v160
	v_cmp_gt_i32_e64 s[0:1], v144, v171
	v_or_b32_e32 v144, 5, v181
	ds_read_b128 v[132:135], v174
	ds_read_b128 v[136:139], v174 offset:64
	ds_read_b128 v[140:143], v174 offset:576
	ds_read_b128 v[128:131], v174 offset:640
	ds_read_b128 v[124:127], v176
	ds_read_b128 v[120:123], v176 offset:1280
	ds_read_b128 v[116:119], v176 offset:2560
	ds_read_b128 v[112:115], v176 offset:3840
	s_and_b64 s[12:13], vcc, s[0:1]
	v_cmp_le_i32_e32 vcc, v144, v160
	v_cmp_gt_i32_e64 s[0:1], v144, v171
	v_or_b32_e32 v148, 6, v181
	s_and_b64 s[16:17], vcc, s[0:1]
	v_cmp_le_i32_e32 vcc, v148, v160
	v_cmp_gt_i32_e64 s[0:1], v148, v171
	v_or_b32_e32 v181, 7, v181
	s_and_b64 s[48:49], vcc, s[0:1]
	v_cmp_le_i32_e32 vcc, v181, v160
	v_cmp_gt_i32_e64 s[0:1], v181, v171
	s_and_b64 s[50:51], vcc, s[0:1]
	s_and_b64 vcc, exec, s[8:9]
	v_mov_b32_e32 v226, 0xff800000
	v_cndmask_b32_e64 v218, v226, 0, s[10:11]
	v_cndmask_b32_e64 v219, v226, 0, s[14:15]
	v_cndmask_b32_e64 v220, v226, 0, s[18:19]
	v_cndmask_b32_e64 v221, v226, 0, s[46:47]
	v_cndmask_b32_e64 v222, v226, 0, s[12:13]
	v_cndmask_b32_e64 v223, v226, 0, s[16:17]
	v_cndmask_b32_e64 v224, v226, 0, s[48:49]
	v_cndmask_b32_e64 v225, v226, 0, s[50:51]
	s_nop 1
	s_cbranch_vccnz .Lmy_fast_w1
	s_waitcnt lgkmcnt(7)
	v_mfma_f32_16x16x32_bf16 v[144:147], v[132:135], v[8:11], v[218:221]
	s_waitcnt lgkmcnt(6)
	v_mfma_f32_16x16x32_bf16 v[148:151], v[136:139], v[12:15], v[144:147]
	s_waitcnt lgkmcnt(5)
	v_mfma_f32_16x16x32_bf16 v[144:147], v[140:143], v[8:11], v[222:225]
	s_waitcnt lgkmcnt(4)
	v_mfma_f32_16x16x32_bf16 v[144:147], v[128:131], v[12:15], v[144:147]
	s_nop 7
	s_cbranch_vccnz .LBB0_760
	v_mul_f32_e32 v181, 0x3e38aa3b, v148
	v_max_f32_e32 v181, 0xf149f2ca, v181
	v_cndmask_b32_e64 v181, v232, v181, s[10:11]
	v_mul_f32_e32 v182, 0x3e38aa3b, v149
	v_max_f32_e32 v182, v181, v182
	v_cndmask_b32_e64 v181, v181, v182, s[14:15]
	v_mul_f32_e32 v182, 0x3e38aa3b, v150
	v_max_f32_e32 v182, v181, v182
	v_cndmask_b32_e64 v181, v181, v182, s[18:19]
	v_mul_f32_e32 v182, 0x3e38aa3b, v151
	v_max_f32_e32 v182, v181, v182
	v_cndmask_b32_e64 v181, v181, v182, s[46:47]
	v_mul_f32_e32 v182, 0x3e38aa3b, v144
	v_max_f32_e32 v182, v181, v182
	v_cndmask_b32_e64 v181, v181, v182, s[12:13]
	v_mul_f32_e32 v182, 0x3e38aa3b, v145
	v_max_f32_e32 v183, v181, v181
	v_max_f32_e32 v182, v183, v182
	v_cndmask_b32_e64 v181, v181, v182, s[16:17]
	v_mul_f32_e32 v182, 0x3e38aa3b, v146
	v_max_f32_e32 v183, v181, v181
	v_max_f32_e32 v182, v183, v182
	v_cndmask_b32_e64 v181, v181, v182, s[48:49]
	v_mul_f32_e32 v182, 0x3e38aa3b, v147
	v_max_f32_e32 v183, v181, v181
	v_max_f32_e32 v182, v183, v182
	v_cndmask_b32_e64 v181, v181, v182, s[50:51]
	ds_bpermute_b32 v182, v175, v181
	v_max_f32_e32 v181, v181, v181
	s_waitcnt lgkmcnt(0)
	v_max_f32_e32 v182, v182, v182
	v_max_f32_e32 v181, v181, v182
	ds_bpermute_b32 v182, v159, v181
	s_waitcnt lgkmcnt(0)
	v_max3_f32 v181, v3, v181, v182
	v_sub_f32_e32 v3, v3, v181
	v_exp_f32_e32 v182, v3
	v_mov_b32_e32 v3, v181
	v_mul_f32_e32 v155, v155, v182
	v_pk_mul_f32 v[102:103], v[102:103], v[182:183] op_sel_hi:[1,0]
	v_pk_mul_f32 v[100:101], v[100:101], v[182:183] op_sel_hi:[1,0]
	v_pk_mul_f32 v[98:99], v[98:99], v[182:183] op_sel_hi:[1,0]
	v_pk_mul_f32 v[96:97], v[96:97], v[182:183] op_sel_hi:[1,0]
	v_pk_mul_f32 v[94:95], v[94:95], v[182:183] op_sel_hi:[1,0]
	v_pk_mul_f32 v[92:93], v[92:93], v[182:183] op_sel_hi:[1,0]
	v_pk_mul_f32 v[90:91], v[90:91], v[182:183] op_sel_hi:[1,0]
	v_pk_mul_f32 v[88:89], v[88:89], v[182:183] op_sel_hi:[1,0]

; #define MFMA16(a, b, c) __builtin_amdgcn_mfma_f32_16x16x32_bf16((a), (b), (c), 0, 0, 0)
; template <int MODE>
; DI void nsa_chunk(const KVFrag& f, int kb, int t, bool selbit, const bf16x8 (&qf)[4][2], f32x4 (&O)[4][4], float (&m)[4], float (&l)[4], int quad, bool online) {
;     ...
;   bool val[8];
; #pragma unroll
;   for (int idx = 0; idx < 8; ++idx) {
;     const int key = kb + 8 * quad + idx;
;     val[idx] = MODE == 0 ? (selbit && key <= t) : (key <= t && key > t - 512);
;   }
; #pragma unroll
;   for (int hh = 0; hh < 4; ++hh) {
;     f32x4 s[2];
; #pragma unroll
;     for (int a = 0; a < 2; ++a) { s[a] = MFMA16(f.k[a][0], qf[hh][0], ((f32x4){0.f, 0.f, 0.f, 0.f})); s[a] = MFMA16(f.k[a][1], qf[hh][1], s[a]); }
;     float mn = m[hh];
;     if (online) {
;       float cm = -1e30f;
; #pragma unroll
;       for (int idx = 0; idx < 8; ++idx) if (val[idx]) cm = fmaxf(cm, s[idx >> 2][idx & 3] * SC);
;       cm = fmaxf(cm, __shfl_xor(cm, 16)); cm = fmaxf(cm, __shfl_xor(cm, 32));
;       mn = fmaxf(mn, cm);
;       const float alpha = __builtin_amdgcn_exp2f(m[hh] - mn);
;       m[hh] = mn; l[hh] *= alpha;
; #pragma unroll
;       for (int dt = 0; dt < 4; ++dt) O[hh][dt] = O[hh][dt] * alpha;
;     }
; template <int MODE>
; DI void nsa_branch(const bf16_t* __restrict__ Kb, const bf16_t* __restrict__ Vtb, unsigned char* lds, int nb, int t, int cur, unsigned selmask, unsigned umall,
;                    const bf16x8 (&qf)[4][2], f32x4 (&O)[4][4], float (&m)[4], float (&l)[4], bool online) {
;     ...
;     *(u32x4*)(slot1 + ldst) = rb;
;     __syncthreads();
;     rb = *(const u32x4*)(gsrc + (long)kbof(min(n + 3, N - 1)) * gmul);
;     if (won) { KVFrag f; nsa_ldsfrag(f, slot1, qi, quad); nsa_chunk<MODE>(f, j * 64 + 32, t, bit, qf, O, m, l, quad, online); }
.LBB0_767:
	s_or_b64 exec, exec, s[56:57]
	v_add_u32_e32 v112, 0x12600, v161
	s_waitcnt vmcnt(1)
	ds_write_b128 v112, v[104:107]
	v_min_i32_e32 v104, s28, v172
	v_lshlrev_b32_e32 v104, 1, v104
	v_and_b32_e32 v104, -4, v104
	v_add_u32_e32 v104, 32, v104
	v_add_u32_e32 v104, 0x14c00, v104
	s_waitcnt lgkmcnt(0)
	s_barrier
	ds_read_b32 v104, v104
	s_waitcnt lgkmcnt(0)
	v_lshl_or_b32 v104, v104, 6, 32
	v_ashrrev_i32_e32 v105, 31, v104
	v_lshlrev_b64 v[104:105], 7, v[104:105]
	v_lshl_add_u64 v[104:105], v[164:165], 0, v[104:105]
	global_load_dwordx4 v[104:107], v[104:105], off
	s_and_saveexec_b64 s[56:57], s[54:55]
	s_cbranch_execz .LBB0_756
	v_lshl_or_b32 v180, v180, 6, v173
	v_cmp_le_i32_e32 vcc, v180, v160
	v_cmp_gt_i32_e64 s[0:1], v180, v171
	s_and_b64 s[10:11], vcc, s[0:1]
	v_cmp_lt_i32_e32 vcc, v180, v160
	v_cmp_ge_i32_e64 s[0:1], v180, v171
	v_or_b32_e32 v144, 2, v180
	s_and_b64 s[14:15], vcc, s[0:1]
	v_cmp_le_i32_e32 vcc, v144, v160
	v_cmp_gt_i32_e64 s[0:1], v144, v171
	v_or_b32_e32 v144, 3, v180
	s_and_b64 s[18:19], vcc, s[0:1]
	v_cmp_le_i32_e32 vcc, v144, v160
	v_cmp_gt_i32_e64 s[0:1], v144, v171
	v_or_b32_e32 v144, 4, v180
	s_and_b64 s[46:47], vcc, s[0:1]
	v_cmp_le_i32_e32 vcc, v144, v160
	v_cmp_gt_i32_e64 s[0:1], v144, v171
	v_or_b32_e32 v144, 5, v180
	ds_read_b128 v[132:135], v177
	ds_read_b128 v[136:139], v177 offset:64
	ds_read_b128 v[140:143], v177 offset:576
	ds_read_b128 v[128:131], v177 offset:640
	ds_read_b128 v[124:127], v178
	ds_read_b128 v[120:123], v178 offset:1280
	ds_read_b128 v[116:119], v178 offset:2560
	ds_read_b128 v[112:115], v178 offset:3840
	s_and_b64 s[12:13], vcc, s[0:1]
	v_cmp_le_i32_e32 vcc, v144, v160
	v_cmp_gt_i32_e64 s[0:1], v144, v171
	v_or_b32_e32 v148, 6, v180
	s_and_b64 s[16:17], vcc, s[0:1]
	v_cmp_le_i32_e32 vcc, v148, v160
	v_cmp_gt_i32_e64 s[0:1], v148, v171
	v_or_b32_e32 v180, 7, v180
	s_and_b64 s[48:49], vcc, s[0:1]
	v_cmp_le_i32_e32 vcc, v180, v160
	v_cmp_gt_i32_e64 s[0:1], v180, v171
	s_and_b64 s[50:51], vcc, s[0:1]
	s_and_b64 vcc, exec, s[8:9]
	v_mov_b32_e32 v226, 0xff800000
	v_cndmask_b32_e64 v218, v226, 0, s[10:11]
	v_cndmask_b32_e64 v219, v226, 0, s[14:15]
	v_cndmask_b32_e64 v220, v226, 0, s[18:19]
	v_cndmask_b32_e64 v221, v226, 0, s[46:47]
	v_cndmask_b32_e64 v222, v226, 0, s[12:13]
	v_cndmask_b32_e64 v223, v226, 0, s[16:17]
	v_cndmask_b32_e64 v224, v226, 0, s[48:49]
	v_cndmask_b32_e64 v225, v226, 0, s[50:51]
	s_nop 1
	s_cbranch_vccnz .Lmy_fast_w2
	s_waitcnt lgkmcnt(7)
	v_mfma_f32_16x16x32_bf16 v[144:147], v[132:135], v[8:11], v[218:221]
	s_waitcnt lgkmcnt(6)
	v_mfma_f32_16x16x32_bf16 v[148:151], v[136:139], v[12:15], v[144:147]
	s_waitcnt lgkmcnt(5)
	v_mfma_f32_16x16x32_bf16 v[144:147], v[140:143], v[8:11], v[222:225]
	s_waitcnt lgkmcnt(4)
	v_mfma_f32_16x16x32_bf16 v[144:147], v[128:131], v[12:15], v[144:147]
	s_nop 7
	s_cbranch_vccnz .LBB0_770
	v_mul_f32_e32 v180, 0x3e38aa3b, v148
	v_max_f32_e32 v180, 0xf149f2ca, v180
	v_cndmask_b32_e64 v180, v232, v180, s[10:11]
	v_mul_f32_e32 v181, 0x3e38aa3b, v149
	v_max_f32_e32 v181, v180, v181
	v_cndmask_b32_e64 v180, v180, v181, s[14:15]
	v_mul_f32_e32 v181, 0x3e38aa3b, v150
	v_max_f32_e32 v181, v180, v181
	v_cndmask_b32_e64 v180, v180, v181, s[18:19]
	v_mul_f32_e32 v181, 0x3e38aa3b, v151
	v_max_f32_e32 v181, v180, v181
	v_cndmask_b32_e64 v180, v180, v181, s[46:47]
	v_mul_f32_e32 v181, 0x3e38aa3b, v144
	v_max_f32_e32 v181, v180, v181
	v_cndmask_b32_e64 v180, v180, v181, s[12:13]
	v_mul_f32_e32 v181, 0x3e38aa3b, v145
	v_max_f32_e32 v182, v180, v180
	v_max_f32_e32 v181, v182, v181
	v_cndmask_b32_e64 v180, v180, v181, s[16:17]
	v_mul_f32_e32 v181, 0x3e38aa3b, v146
	v_max_f32_e32 v182, v180, v180
	v_max_f32_e32 v181, v182, v181
	v_cndmask_b32_e64 v180, v180, v181, s[48:49]
	v_mul_f32_e32 v181, 0x3e38aa3b, v147
	v_max_f32_e32 v182, v180, v180
	v_max_f32_e32 v181, v182, v181
	v_cndmask_b32_e64 v180, v180, v181, s[50:51]
	ds_bpermute_b32 v181, v175, v180
	v_max_f32_e32 v180, v180, v180
	s_waitcnt lgkmcnt(0)
	v_max_f32_e32 v181, v181, v181
	v_max_f32_e32 v180, v180, v181
	ds_bpermute_b32 v181, v159, v180
	s_waitcnt lgkmcnt(0)
	v_max3_f32 v181, v3, v180, v181
	v_sub_f32_e32 v3, v3, v181
	v_exp_f32_e32 v180, v3
	v_mov_b32_e32 v3, v181
	v_mul_f32_e32 v155, v155, v180
	v_pk_mul_f32 v[102:103], v[102:103], v[180:181] op_sel_hi:[1,0]
	v_pk_mul_f32 v[100:101], v[100:101], v[180:181] op_sel_hi:[1,0]
	v_pk_mul_f32 v[98:99], v[98:99], v[180:181] op_sel_hi:[1,0]
	v_pk_mul_f32 v[96:97], v[96:97], v[180:181] op_sel_hi:[1,0]
	v_pk_mul_f32 v[94:95], v[94:95], v[180:181] op_sel_hi:[1,0]
	v_pk_mul_f32 v[92:93], v[92:93], v[180:181] op_sel_hi:[1,0]
	v_pk_mul_f32 v[90:91], v[90:91], v[180:181] op_sel_hi:[1,0]
	v_pk_mul_f32 v[88:89], v[88:89], v[180:181] op_sel_hi:[1,0]

; #define MFMA16(a, b, c) __builtin_amdgcn_mfma_f32_16x16x32_bf16((a), (b), (c), 0, 0, 0)
; DI unsigned pk2(float lo, float hi) { f32x2 v = {lo, hi}; bf16x2_t b = __builtin_convertvector(v, bf16x2_t); return __builtin_bit_cast(unsigned, b); }
; template <int MODE>
; DI void nsa_chunk(const KVFrag& f, int kb, int t, bool selbit, const bf16x8 (&qf)[4][2], f32x4 (&O)[4][4], float (&m)[4], float (&l)[4], int quad, bool online) {
;     ...
;   for (int hh = 0; hh < 4; ++hh) {
;     f32x4 s[2];
; #pragma unroll
;     for (int a = 0; a < 2; ++a) { s[a] = MFMA16(f.k[a][0], qf[hh][0], ((f32x4){0.f, 0.f, 0.f, 0.f})); s[a] = MFMA16(f.k[a][1], qf[hh][1], s[a]); }
;     float mn = m[hh];
;     if (online) {
;       float cm = -1e30f;
; #pragma unroll
;       for (int idx = 0; idx < 8; ++idx) if (val[idx]) cm = fmaxf(cm, s[idx >> 2][idx & 3] * SC);
;       cm = fmaxf(cm, __shfl_xor(cm, 16)); cm = fmaxf(cm, __shfl_xor(cm, 32));
;       mn = fmaxf(mn, cm);
;       const float alpha = __builtin_amdgcn_exp2f(m[hh] - mn);
;       m[hh] = mn; l[hh] *= alpha;
; #pragma unroll
;       for (int dt = 0; dt < 4; ++dt) O[hh][dt] = O[hh][dt] * alpha;
;     }
;     float pv[8]; float ps = 0.f;
; #pragma unroll
;     for (int idx = 0; idx < 8; ++idx) { pv[idx] = val[idx] ? __builtin_amdgcn_exp2f(fmaf(s[idx >> 2][idx & 3], SC, -mn)) : 0.f; ps += pv[idx]; }
;     l[hh] += ps;
;     const bf16x8 pf = mk8((u32x4){pk2(pv[0], pv[1]), pk2(pv[2], pv[3]), pk2(pv[4], pv[5]), pk2(pv[6], pv[7])});
; #pragma unroll
;     for (int dt = 0; dt < 4; ++dt) O[hh][dt] = MFMA16(f.v[dt], pf, O[hh][dt]);
;   }
.Lmy_fast_w1:
	s_waitcnt lgkmcnt(4)
	v_mfma_f32_16x16x32_bf16 v[182:185], v[132:135], v[8:11], v[218:221]
	v_mfma_f32_16x16x32_bf16 v[182:185], v[136:139], v[12:15], v[182:185]
	v_mfma_f32_16x16x32_bf16 v[186:189], v[140:143], v[8:11], v[222:225]
	v_mfma_f32_16x16x32_bf16 v[186:189], v[128:131], v[12:15], v[186:189]
	v_mfma_f32_16x16x32_bf16 v[190:193], v[132:135], v[16:19], v[218:221]
	v_mfma_f32_16x16x32_bf16 v[190:193], v[136:139], v[20:23], v[190:193]
	v_mfma_f32_16x16x32_bf16 v[194:197], v[140:143], v[16:19], v[222:225]
	v_mfma_f32_16x16x32_bf16 v[194:197], v[128:131], v[20:23], v[194:197]
	s_waitcnt lgkmcnt(0)
	s_nop 2
	v_pk_fma_f32 v[240:241], v[182:183], s[34:35], v[2:3] op_sel:[0,0,1] op_sel_hi:[1,0,1] neg_lo:[0,0,1] neg_hi:[0,0,1]
	v_pk_fma_f32 v[242:243], v[184:185], s[34:35], v[2:3] op_sel:[0,0,1] op_sel_hi:[1,0,1] neg_lo:[0,0,1] neg_hi:[0,0,1]
	v_pk_fma_f32 v[244:245], v[186:187], s[34:35], v[2:3] op_sel:[0,0,1] op_sel_hi:[1,0,1] neg_lo:[0,0,1] neg_hi:[0,0,1]
	v_pk_fma_f32 v[246:247], v[188:189], s[34:35], v[2:3] op_sel:[0,0,1] op_sel_hi:[1,0,1] neg_lo:[0,0,1] neg_hi:[0,0,1]
	v_exp_f32_e32 v240, v240
	v_exp_f32_e32 v241, v241
	v_mfma_f32_16x16x32_bf16 v[182:185], v[132:135], v[24:27], v[218:221]
	v_exp_f32_e32 v242, v242
	v_exp_f32_e32 v243, v243
	v_mfma_f32_16x16x32_bf16 v[182:185], v[136:139], v[28:31], v[182:185]
	v_exp_f32_e32 v244, v244
	v_exp_f32_e32 v245, v245
	v_mfma_f32_16x16x32_bf16 v[186:189], v[140:143], v[24:27], v[222:225]
	v_exp_f32_e32 v246, v246
	v_exp_f32_e32 v247, v247
	v_mfma_f32_16x16x32_bf16 v[186:189], v[128:131], v[28:31], v[186:189]
	v_cvt_pk_bf16_f32 v248, v240, v241
	v_cvt_pk_bf16_f32 v249, v242, v243
	v_cvt_pk_bf16_f32 v250, v244, v245
	v_cvt_pk_bf16_f32 v251, v246, v247
	v_add_f32_e32 v205, 0, v240
	v_add_f32_e32 v205, v241, v205
	v_add_f32_e32 v205, v242, v205
	v_add_f32_e32 v205, v243, v205
	v_add_f32_e32 v205, v244, v205
	v_add_f32_e32 v205, v245, v205
	v_add_f32_e32 v205, v246, v205
	v_add_f32_e32 v205, v247, v205
	v_add_f32_e32 v155, v155, v205
	v_pk_fma_f32 v[240:241], v[190:191], s[34:35], v[2:3] op_sel_hi:[1,0,0] neg_lo:[0,0,1] neg_hi:[0,0,1]
	v_pk_fma_f32 v[242:243], v[192:193], s[34:35], v[2:3] op_sel_hi:[1,0,0] neg_lo:[0,0,1] neg_hi:[0,0,1]
	v_pk_fma_f32 v[244:245], v[194:195], s[34:35], v[2:3] op_sel_hi:[1,0,0] neg_lo:[0,0,1] neg_hi:[0,0,1]
	v_pk_fma_f32 v[246:247], v[196:197], s[34:35], v[2:3] op_sel_hi:[1,0,0] neg_lo:[0,0,1] neg_hi:[0,0,1]
	v_exp_f32_e32 v240, v240
	v_exp_f32_e32 v241, v241
	v_mfma_f32_16x16x32_bf16 v[190:193], v[132:135], v[32:35], v[218:221]
	v_exp_f32_e32 v242, v242
	v_exp_f32_e32 v243, v243
	v_mfma_f32_16x16x32_bf16 v[190:193], v[136:139], v[36:39], v[190:193]
	v_exp_f32_e32 v244, v244
	v_exp_f32_e32 v245, v245
	v_mfma_f32_16x16x32_bf16 v[194:197], v[140:143], v[32:35], v[222:225]
	v_exp_f32_e32 v246, v246
	v_exp_f32_e32 v247, v247
	v_mfma_f32_16x16x32_bf16 v[194:197], v[128:131], v[36:39], v[194:197]
	v_cvt_pk_bf16_f32 v198, v240, v241
	v_cvt_pk_bf16_f32 v199, v242, v243
	v_mfma_f32_16x16x32_bf16 v[100:103], v[124:127], v[248:251], v[100:103]
	v_cvt_pk_bf16_f32 v200, v244, v245
	v_cvt_pk_bf16_f32 v201, v246, v247
	v_mfma_f32_16x16x32_bf16 v[96:99], v[120:123], v[248:251], v[96:99]
	v_add_f32_e32 v205, 0, v240
	v_add_f32_e32 v205, v241, v205
	v_mfma_f32_16x16x32_bf16 v[92:95], v[116:119], v[248:251], v[92:95]
	v_add_f32_e32 v205, v242, v205
	v_add_f32_e32 v205, v243, v205
	v_mfma_f32_16x16x32_bf16 v[88:91], v[112:115], v[248:251], v[88:91]
	v_add_f32_e32 v205, v244, v205
	v_add_f32_e32 v205, v245, v205
	v_add_f32_e32 v205, v246, v205
	v_add_f32_e32 v205, v247, v205
	v_add_f32_e32 v154, v154, v205
	v_pk_fma_f32 v[240:241], v[182:183], s[34:35], v[0:1] op_sel_hi:[1,0,0] neg_lo:[0,0,1] neg_hi:[0,0,1]
	v_pk_fma_f32 v[242:243], v[184:185], s[34:35], v[0:1] op_sel_hi:[1,0,0] neg_lo:[0,0,1] neg_hi:[0,0,1]
	v_pk_fma_f32 v[244:245], v[186:187], s[34:35], v[0:1] op_sel_hi:[1,0,0] neg_lo:[0,0,1] neg_hi:[0,0,1]
	v_pk_fma_f32 v[246:247], v[188:189], s[34:35], v[0:1] op_sel_hi:[1,0,0] neg_lo:[0,0,1] neg_hi:[0,0,1]
	v_exp_f32_e32 v240, v240
	v_exp_f32_e32 v241, v241
	v_mfma_f32_16x16x32_bf16 v[84:87], v[124:127], v[198:201], v[84:87]
	v_exp_f32_e32 v242, v242
	v_exp_f32_e32 v243, v243
	v_mfma_f32_16x16x32_bf16 v[80:83], v[120:123], v[198:201], v[80:83]
	v_exp_f32_e32 v244, v244
	v_exp_f32_e32 v245, v245
	v_mfma_f32_16x16x32_bf16 v[76:79], v[116:119], v[198:201], v[76:79]
	v_exp_f32_e32 v246, v246
	v_exp_f32_e32 v247, v247
	v_mfma_f32_16x16x32_bf16 v[72:75], v[112:115], v[198:201], v[72:75]
	v_cvt_pk_bf16_f32 v248, v240, v241
	v_cvt_pk_bf16_f32 v249, v242, v243
	v_cvt_pk_bf16_f32 v250, v244, v245
	v_cvt_pk_bf16_f32 v251, v246, v247
	v_add_f32_e32 v205, 0, v240
	v_add_f32_e32 v205, v241, v205
	v_add_f32_e32 v205, v242, v205
	v_add_f32_e32 v205, v243, v205
	v_add_f32_e32 v205, v244, v205
	v_add_f32_e32 v205, v245, v205
	v_add_f32_e32 v205, v246, v205
	v_add_f32_e32 v205, v247, v205
	v_add_f32_e32 v153, v153, v205
	v_pk_fma_f32 v[240:241], v[190:191], s[34:35], v[178:179] op_sel:[0,0,1] op_sel_hi:[1,0,1] neg_lo:[0,0,1] neg_hi:[0,0,1]
	v_pk_fma_f32 v[242:243], v[192:193], s[34:35], v[178:179] op_sel:[0,0,1] op_sel_hi:[1,0,1] neg_lo:[0,0,1] neg_hi:[0,0,1]
	v_pk_fma_f32 v[244:245], v[194:195], s[34:35], v[178:179] op_sel:[0,0,1] op_sel_hi:[1,0,1] neg_lo:[0,0,1] neg_hi:[0,0,1]
	v_pk_fma_f32 v[246:247], v[196:197], s[34:35], v[178:179] op_sel:[0,0,1] op_sel_hi:[1,0,1] neg_lo:[0,0,1] neg_hi:[0,0,1]
	v_exp_f32_e32 v240, v240
	v_exp_f32_e32 v241, v241
	v_mfma_f32_16x16x32_bf16 v[68:71], v[124:127], v[248:251], v[68:71]
	v_exp_f32_e32 v242, v242
	v_exp_f32_e32 v243, v243
	v_mfma_f32_16x16x32_bf16 v[64:67], v[120:123], v[248:251], v[64:67]
	v_exp_f32_e32 v244, v244
	v_exp_f32_e32 v245, v245
	v_mfma_f32_16x16x32_bf16 v[60:63], v[116:119], v[248:251], v[60:63]
	v_exp_f32_e32 v246, v246
	v_exp_f32_e32 v247, v247
	v_mfma_f32_16x16x32_bf16 v[56:59], v[112:115], v[248:251], v[56:59]
	v_cvt_pk_bf16_f32 v198, v240, v241
	v_cvt_pk_bf16_f32 v199, v242, v243
	v_cvt_pk_bf16_f32 v200, v244, v245
	v_cvt_pk_bf16_f32 v201, v246, v247
	v_add_f32_e32 v205, 0, v240
	v_add_f32_e32 v205, v241, v205
	v_add_f32_e32 v205, v242, v205
	v_add_f32_e32 v205, v243, v205
	v_add_f32_e32 v205, v244, v205
	v_add_f32_e32 v205, v245, v205
	v_add_f32_e32 v205, v246, v205
	v_add_f32_e32 v205, v247, v205
	v_add_f32_e32 v152, v152, v205
	s_nop 0
	v_mfma_f32_16x16x32_bf16 v[52:55], v[124:127], v[198:201], v[52:55]
	v_mfma_f32_16x16x32_bf16 v[48:51], v[120:123], v[198:201], v[48:51]
	v_mfma_f32_16x16x32_bf16 v[44:47], v[116:119], v[198:201], v[44:47]
	v_mfma_f32_16x16x32_bf16 v[40:43], v[112:115], v[198:201], v[40:43]
	s_branch .LBB0_767
